# attention: s_setprio 1 around the dependent QK MFMA chain (the GEMM loops already do this; attention did not)
# speedup vs baseline: 1.0059x; 1.0022x over previous
; template <int DK, bool PF>
; DEV void attn_item(const u16* __restrict__ qrow, const u16* __restrict__ ka, int ldka, const u16* __restrict__ kb, int ldkb,
;                    const u16* __restrict__ vt, int ldvt, int ntiles, int my_tiles, int kvlen, u16* orow,
;                    unsigned char* smem) {
;     ...
;         const u16* kp = sK + (mi * 32 + l31) * KST + hh * 8;
;         constexpr int KB = QREG ? 12 : 4;
; #pragma unroll
;         for (int k0 = 0; k0 < DK / 16; k0 += KB) {
;           bf16x8 kf[KB];
; #pragma unroll
;           for (int i = 0; i < KB; ++i) kf[i] = *(const bf16x8*)(kp + (k0 + i) * 16);
;           __builtin_amdgcn_sched_barrier(0);
; #pragma unroll
;           for (int i = 0; i < KB; ++i) {
;             bf16x8 qv;
;             if (QREG) qv = qf[k0 + i];
;             else qv = *(const bf16x8*)(qp + (k0 + i) * 16);
;             s = __builtin_amdgcn_mfma_f32_32x32x16_bf16(kf[i], qv, s, 0, 0, 0);
;           }
;         }
;         bf16x8 vf[8];
;         {
;           const u16* vp = sV + l31 * VST + mi * 32 + 4 * hh;
; #pragma unroll
;           for (int oc = 0; oc < 2; ++oc)
; #pragma unroll
;             for (int d = 0; d < 4; ++d) {
;               union { bf16x8 v; uint2 u[2]; } cv;
;               cv.u[0] = *(const uint2*)(vp + d * 32 * VST + oc * 16);
;               cv.u[1] = *(const uint2*)(vp + d * 32 * VST + oc * 16 + 8);
;               vf[oc * 4 + d] = cv.v;
;             }
;           __builtin_amdgcn_sched_barrier(0);
;         }
;         if (key0 + 64 > kvlen) {
; #pragma unroll
;           for (int r = 0; r < 16; ++r) {
;             int key = key0 + mi * 32 + (r & 3) + 8 * (r >> 2) + 4 * hh;
;             if (key >= kvlen) s[r] = -1e30f;
;           }
;         }
;         float mx = -1e30f;
; #pragma unroll
;         for (int r = 0; r < 16; ++r) mx = fmaxf(mx, s[r]);
;         mx = fmaxf(mx, __shfl_xor(mx, 32, 64));
;         if (__builtin_amdgcn_ballot_w64(mx > mrun) != 0ull) {
;           const float mnew = fmaxf(mrun, mx);
;           const float alpha = __builtin_amdgcn_exp2f(mrun - mnew);
;           mrun = mnew;
;           lrun *= alpha;
; #pragma unroll
;           for (int d = 0; d < 4; ++d)
; #pragma unroll
;             for (int r = 0; r < 16; ++r) o[d][r] *= alpha;
;         }
.LBB0_1021:
	v_or_b32_e32 v64, s13, v217
	v_mad_u32_u24 v68, v64, s54, v224
	ds_read_b128 v[64:67], v68
	ds_read_b128 v[168:171], v68 offset:32
	ds_read_b128 v[172:175], v68 offset:64
	ds_read_b128 v[176:179], v68 offset:96
	ds_read_b128 v[180:183], v68 offset:128
	ds_read_b128 v[184:187], v68 offset:160
	ds_read_b128 v[188:191], v68 offset:192
	ds_read_b128 v[192:195], v68 offset:224
	ds_read_b128 v[196:199], v68 offset:256
	ds_read_b128 v[226:229], v68 offset:288
	ds_read_b128 v[248:251], v68 offset:320
	ds_read_b128 v[234:237], v68 offset:352
	s_setprio 1
	s_waitcnt lgkmcnt(11)
	v_mfma_f32_32x32x16_bf16 v[64:79], v[64:67], v[80:83], 0
	s_waitcnt lgkmcnt(10)
	v_mfma_f32_32x32x16_bf16 v[64:79], v[168:171], v[84:87], v[64:79]
	v_lshl_add_u32 v168, s13, 1, v213
	v_add_u32_e32 v169, 0x6000, v168
	v_add_u32_e32 v170, 0x8000, v168
	s_waitcnt lgkmcnt(9)
	v_mfma_f32_32x32x16_bf16 v[64:79], v[172:175], v[88:91], v[64:79]
	s_waitcnt lgkmcnt(8)
	v_mfma_f32_32x32x16_bf16 v[64:79], v[176:179], v[92:95], v[64:79]
	s_waitcnt lgkmcnt(7)
	v_mfma_f32_32x32x16_bf16 v[64:79], v[180:183], v[96:99], v[64:79]
	s_waitcnt lgkmcnt(6)
	v_mfma_f32_32x32x16_bf16 v[64:79], v[184:187], v[100:103], v[64:79]
	s_waitcnt lgkmcnt(5)
	v_mfma_f32_32x32x16_bf16 v[64:79], v[188:191], v[104:107], v[64:79]
	s_waitcnt lgkmcnt(4)
	v_mfma_f32_32x32x16_bf16 v[64:79], v[192:195], v[108:111], v[64:79]
	ds_read2_b64 v[192:195], v169 offset0:128 offset1:130
	ds_read2_b64 v[176:179], v169 offset0:132 offset1:134
	v_add_u32_e32 v169, 0x7000, v168
	v_add_u32_e32 v168, 0x9000, v168
	ds_read2_b64 v[188:191], v170 offset0:192 offset1:194
	s_waitcnt lgkmcnt(6)
	v_mfma_f32_32x32x16_bf16 v[64:79], v[196:199], v[112:115], v[64:79]
	ds_read2_b64 v[196:199], v169 offset0:160 offset1:162
	ds_read2_b64 v[184:187], v168 offset0:224 offset1:226
	ds_read2_b64 v[180:183], v169 offset0:164 offset1:166
	ds_read2_b64 v[172:175], v170 offset0:196 offset1:198
	ds_read2_b64 v[168:171], v168 offset0:228 offset1:230
	s_waitcnt lgkmcnt(10)
	v_mfma_f32_32x32x16_bf16 v[64:79], v[226:229], v[116:119], v[64:79]
	s_waitcnt lgkmcnt(9)
	v_mfma_f32_32x32x16_bf16 v[64:79], v[248:251], v[120:123], v[64:79]
	s_waitcnt lgkmcnt(8)
	v_mfma_f32_32x32x16_bf16 v[64:79], v[234:237], v[124:127], v[64:79]
	s_setprio 0
	s_nop 10
	v_max3_f32 v221, v64, s53, v65
	v_max3_f32 v221, v221, v66, v67
	v_max3_f32 v221, v221, v68, v69
	v_max3_f32 v221, v221, v70, v71
	v_max3_f32 v221, v221, v72, v73
	v_max3_f32 v221, v221, v74, v75
	v_max3_f32 v221, v221, v76, v77
	v_max3_f32 v221, v221, v78, v79
	ds_bpermute_b32 v222, v220, v221
	s_waitcnt lgkmcnt(0)
	v_max_f32_e32 v222, v222, v222
	v_max_f32_e32 v221, v221, v222
	v_cmp_gt_f32_e32 vcc, v221, v219
	s_cbranch_vccz .LBB0_1020
	v_max_f32_e32 v221, v221, v221
	v_max_f32_e32 v222, v219, v219
	v_max_f32_e32 v221, v222, v221
	v_sub_f32_e32 v219, v219, v221
	v_exp_f32_e32 v222, v219
	v_mov_b32_e32 v219, v221
	v_pk_mul_f32 v[62:63], v[62:63], v[222:223] op_sel_hi:[1,0]
	v_pk_mul_f32 v[60:61], v[60:61], v[222:223] op_sel_hi:[1,0]
	v_pk_mul_f32 v[58:59], v[58:59], v[222:223] op_sel_hi:[1,0]
	v_pk_mul_f32 v[56:57], v[56:57], v[222:223] op_sel_hi:[1,0]
	v_pk_mul_f32 v[54:55], v[54:55], v[222:223] op_sel_hi:[1,0]
	v_pk_mul_f32 v[52:53], v[52:53], v[222:223] op_sel_hi:[1,0]
	v_pk_mul_f32 v[50:51], v[50:51], v[222:223] op_sel_hi:[1,0]
	v_pk_mul_f32 v[48:49], v[48:49], v[222:223] op_sel_hi:[1,0]
	v_pk_mul_f32 v[46:47], v[46:47], v[222:223] op_sel_hi:[1,0]
	v_pk_mul_f32 v[44:45], v[44:45], v[222:223] op_sel_hi:[1,0]
	v_pk_mul_f32 v[42:43], v[42:43], v[222:223] op_sel_hi:[1,0]
	v_pk_mul_f32 v[40:41], v[40:41], v[222:223] op_sel_hi:[1,0]
	v_pk_mul_f32 v[38:39], v[38:39], v[222:223] op_sel_hi:[1,0]
	v_pk_mul_f32 v[36:37], v[36:37], v[222:223] op_sel_hi:[1,0]
	v_pk_mul_f32 v[34:35], v[34:35], v[222:223] op_sel_hi:[1,0]
	v_pk_mul_f32 v[32:33], v[32:33], v[222:223] op_sel_hi:[1,0]
	v_pk_mul_f32 v[30:31], v[30:31], v[222:223] op_sel_hi:[1,0]
	v_pk_mul_f32 v[28:29], v[28:29], v[222:223] op_sel_hi:[1,0]
	v_pk_mul_f32 v[26:27], v[26:27], v[222:223] op_sel_hi:[1,0]
	v_pk_mul_f32 v[24:25], v[24:25], v[222:223] op_sel_hi:[1,0]
	v_pk_mul_f32 v[22:23], v[22:23], v[222:223] op_sel_hi:[1,0]
	v_pk_mul_f32 v[20:21], v[20:21], v[222:223] op_sel_hi:[1,0]
	v_pk_mul_f32 v[18:19], v[18:19], v[222:223] op_sel_hi:[1,0]
	v_pk_mul_f32 v[16:17], v[16:17], v[222:223] op_sel_hi:[1,0]
	v_pk_mul_f32 v[14:15], v[14:15], v[222:223] op_sel_hi:[1,0]
	v_pk_mul_f32 v[12:13], v[12:13], v[222:223] op_sel_hi:[1,0]
	v_pk_mul_f32 v[10:11], v[10:11], v[222:223] op_sel_hi:[1,0]
	v_pk_mul_f32 v[8:9], v[8:9], v[222:223] op_sel_hi:[1,0]
	v_pk_mul_f32 v[6:7], v[6:7], v[222:223] op_sel_hi:[1,0]
	v_pk_mul_f32 v[4:5], v[4:5], v[222:223] op_sel_hi:[1,0]
	v_pk_mul_f32 v[2:3], v[2:3], v[222:223] op_sel_hi:[1,0]
	v_pk_mul_f32 v[0:1], v[0:1], v[222:223] op_sel_hi:[1,0]
	v_mul_f32_e32 v215, v215, v222
	s_branch .LBB0_1020
